# pebias item: 16 w1 loads per iteration issued together instead of 16 serialized round trips
# baseline (speedup 1.0000x reference)
; DI int TID() { int t = threadIdx.x; asm volatile("" : "+v"(t)); return t; }
; DI void conv_item_B(const Params& p, int L, int it, char* smem) {
;     ...
;     const int q = it - 180; const int kv = q >> 3, kr = q & 7; const int tid = TID(); const int n = tid & 63, kq = tid >> 6;
;     const float* w1 = (kv ? p.nsa_w1_v : p.nsa_w1_k) + (size_t)L * 2048 * 64;
;     const float* pe = (kv ? p.nsa_pe_v : p.nsa_pe_k) + (size_t)L * 2048;
;     float a = 0.f;
;     const int kb = kr * 256 + kq * 64;
; #pragma unroll 16
;     for (int k = kb; k < kb + 64; ++k) a += pe[k] * w1[(size_t)k * 64 + n];
;     float* red = (float*)smem;
;     __syncthreads(); red[tid] = a; __syncthreads();
;     if (tid < 64) p.pebias[(kv * 8 + kr) * 64 + tid] = (red[tid] + red[tid + 64]) + (red[tid + 128] + red[tid + 192]);
;   }
.LBB0_32:
	global_load_dwordx4 v[8:11], v[0:1], off offset:-12
	global_load_dwordx4 v[12:15], v[0:1], off offset:-28
	global_load_dwordx4 v[16:19], v[0:1], off offset:-44
	global_load_dwordx4 v[20:23], v[0:1], off offset:-60
	global_load_dword v24, v[2:3], off offset:-2048
	global_load_dword v25, v[2:3], off offset:-1792
	global_load_dword v210, v[2:3], off offset:-1536
	global_load_dword v211, v[2:3], off offset:-1280
	global_load_dword v240, v[2:3], off offset:-1024
	global_load_dword v241, v[2:3], off offset:-768
	global_load_dword v242, v[2:3], off offset:-512
	global_load_dword v243, v[2:3], off offset:-256
	global_load_dword v244, v[2:3], off
	global_load_dword v245, v[2:3], off offset:256
	global_load_dword v246, v[2:3], off offset:512
	global_load_dword v247, v[2:3], off offset:768
	global_load_dword v248, v[2:3], off offset:1024
	global_load_dword v249, v[2:3], off offset:1280
	global_load_dword v250, v[2:3], off offset:1536
	global_load_dword v251, v[2:3], off offset:1792
	v_add_u32_e32 v6, 16, v6
	v_cmp_ge_i32_e32 vcc, v6, v5
	v_lshl_add_u64 v[0:1], v[0:1], 0, 64
	s_or_b64 s[2:3], vcc, s[2:3]
	v_lshl_add_u64 v[2:3], v[2:3], 0, s[16:17]
	s_waitcnt vmcnt(0)
	v_fmac_f32_e32 v7, v20, v24
	v_fmac_f32_e32 v7, v21, v25
	v_fmac_f32_e32 v7, v22, v210
	v_fmac_f32_e32 v7, v23, v211
	v_fmac_f32_e32 v7, v16, v240
	v_fmac_f32_e32 v7, v17, v241
	v_fmac_f32_e32 v7, v18, v242
	v_fmac_f32_e32 v7, v19, v243
	v_fmac_f32_e32 v7, v12, v244
	v_fmac_f32_e32 v7, v13, v245
	v_fmac_f32_e32 v7, v14, v246
	v_fmac_f32_e32 v7, v15, v247
	v_fmac_f32_e32 v7, v8, v248
	v_fmac_f32_e32 v7, v9, v249
	v_fmac_f32_e32 v7, v10, v250
	v_fmac_f32_e32 v7, v11, v251
	s_andn2_b64 exec, exec, s[2:3]
	s_cbranch_execnz .LBB0_32
	s_or_b64 exec, exec, s[2:3]
	v_lshlrev_b32_e32 v0, 2, v4
	v_cmp_gt_i32_e32 vcc, 64, v4
	s_barrier
	ds_write_b32 v0, v7
	s_waitcnt lgkmcnt(0)
	s_barrier
	s_and_saveexec_b64 s[2:3], vcc
	s_cbranch_execz .LBB0_35
	ds_read2st64_b32 v[2:3], v0 offset1:1
	ds_read2st64_b32 v[0:1], v0 offset0:2 offset1:3
	v_readlane_b32 s16, v254, 30
	v_readlane_b32 s18, v254, 32
	v_readlane_b32 s19, v254, 33
	s_waitcnt lgkmcnt(1)
	v_mov_b32_e32 v6, v2
	s_waitcnt lgkmcnt(0)
	v_mov_b32_e32 v7, v0
	v_mov_b32_e32 v0, v3
	v_pk_add_f32 v[0:1], v[6:7], v[0:1]
	v_readlane_b32 s17, v254, 31
	v_add_f32_e32 v2, v0, v1
	v_lshl_add_u32 v0, s4, 6, v4
	v_ashrrev_i32_e32 v1, 31, v0
	v_lshl_add_u64 v[0:1], v[0:1], 2, s[18:19]
	global_store_dword v[0:1], v2, off

; DI int TID() { int t = threadIdx.x; asm volatile("" : "+v"(t)); return t; }
; DI void conv_item_B(const Params& p, int L, int it, char* smem) {
;     ...
;     const int q = it - 180; const int kv = q >> 3, kr = q & 7; const int tid = TID(); const int n = tid & 63, kq = tid >> 6;
;     const float* w1 = (kv ? p.nsa_w1_v : p.nsa_w1_k) + (size_t)L * 2048 * 64;
;     const float* pe = (kv ? p.nsa_pe_v : p.nsa_pe_k) + (size_t)L * 2048;
;     float a = 0.f;
;     const int kb = kr * 256 + kq * 64;
; #pragma unroll 16
;     for (int k = kb; k < kb + 64; ++k) a += pe[k] * w1[(size_t)k * 64 + n];
;     float* red = (float*)smem;
;     __syncthreads(); red[tid] = a; __syncthreads();
;     if (tid < 64) p.pebias[(kv * 8 + kr) * 64 + tid] = (red[tid] + red[tid + 64]) + (red[tid + 128] + red[tid + 192]);
;   }
; DI void phase_ple(const Params& p, int L, char* smem) {
;     ...
;     for (int it = blockIdx.x; it < CV_NA + CV_NB; it += gridDim.x) {
;       if (it < CV_NA) conv_item_A(p, L + 1, it, smem); else conv_item_B(p, L + 1, it - CV_NA, smem);
.LBB0_1957:
	global_load_dwordx4 v[8:11], v[0:1], off offset:-12
	global_load_dwordx4 v[12:15], v[0:1], off offset:-28
	global_load_dwordx4 v[16:19], v[0:1], off offset:-44
	global_load_dwordx4 v[20:23], v[0:1], off offset:-60
	global_load_dword v24, v[2:3], off offset:-2048
	global_load_dword v25, v[2:3], off offset:-1792
	global_load_dword v210, v[2:3], off offset:-1536
	global_load_dword v211, v[2:3], off offset:-1280
	global_load_dword v240, v[2:3], off offset:-1024
	global_load_dword v241, v[2:3], off offset:-768
	global_load_dword v242, v[2:3], off offset:-512
	global_load_dword v243, v[2:3], off offset:-256
	global_load_dword v244, v[2:3], off
	global_load_dword v245, v[2:3], off offset:256
	global_load_dword v246, v[2:3], off offset:512
	global_load_dword v247, v[2:3], off offset:768
	global_load_dword v248, v[2:3], off offset:1024
	global_load_dword v249, v[2:3], off offset:1280
	global_load_dword v250, v[2:3], off offset:1536
	global_load_dword v251, v[2:3], off offset:1792
	v_add_u32_e32 v6, 16, v6
	v_cmp_ge_i32_e32 vcc, v6, v5
	v_lshl_add_u64 v[0:1], v[0:1], 0, 64
	s_or_b64 s[2:3], vcc, s[2:3]
	v_lshl_add_u64 v[2:3], v[2:3], 0, s[54:55]
	s_waitcnt vmcnt(0)
	v_fmac_f32_e32 v7, v20, v24
	v_fmac_f32_e32 v7, v21, v25
	v_fmac_f32_e32 v7, v22, v210
	v_fmac_f32_e32 v7, v23, v211
	v_fmac_f32_e32 v7, v16, v240
	v_fmac_f32_e32 v7, v17, v241
	v_fmac_f32_e32 v7, v18, v242
	v_fmac_f32_e32 v7, v19, v243
	v_fmac_f32_e32 v7, v12, v244
	v_fmac_f32_e32 v7, v13, v245
	v_fmac_f32_e32 v7, v14, v246
	v_fmac_f32_e32 v7, v15, v247
	v_fmac_f32_e32 v7, v8, v248
	v_fmac_f32_e32 v7, v9, v249
	v_fmac_f32_e32 v7, v10, v250
	v_fmac_f32_e32 v7, v11, v251
	s_andn2_b64 exec, exec, s[2:3]
	s_cbranch_execnz .LBB0_1957
	s_or_b64 exec, exec, s[2:3]
	v_lshlrev_b32_e32 v0, 2, v4
	v_cmp_gt_i32_e32 vcc, 64, v4
	s_barrier
	ds_write_b32 v0, v7
	s_waitcnt lgkmcnt(0)
	s_barrier
	s_and_saveexec_b64 s[2:3], vcc
	s_cbranch_execz .LBB0_1960
	ds_read2st64_b32 v[2:3], v0 offset1:1
	ds_read2st64_b32 v[0:1], v0 offset0:2 offset1:3
	v_readlane_b32 s16, v254, 30
	v_readlane_b32 s18, v254, 32
	v_readlane_b32 s19, v254, 33
	s_waitcnt lgkmcnt(1)
	v_mov_b32_e32 v6, v2
	s_waitcnt lgkmcnt(0)
	v_mov_b32_e32 v7, v0
	v_mov_b32_e32 v0, v3
	v_pk_add_f32 v[0:1], v[6:7], v[0:1]
	v_readlane_b32 s17, v254, 31
	v_add_f32_e32 v2, v0, v1
	v_lshl_add_u32 v0, s4, 6, v4
	v_ashrrev_i32_e32 v1, 31, v0
	v_lshl_add_u64 v[0:1], v[0:1], 2, s[18:19]
	global_store_dword v[0:1], v2, off
